# in-proj K-loop: issue each load segment's LDS-DMA before its ds_reads (earlier landing relative to the covering wait)
# speedup vs baseline: 1.0073x; 1.0073x over previous
; #define PG8_STAGE(bufoff, gbase, voff) do { _Pragma("unroll") for (int _i = 0; _i < 2; ++_i) \
;         __builtin_amdgcn_global_load_lds((const unsigned*)((const char*)(gbase) + (voff)[_i]), (PG8_LAS unsigned*)(lds + (bufoff) + ldsw + _i * 8192), 16, 0, 0); } while (0)
; #define PG8_LDA(dst, b, h) do { _Pragma("unroll") for (int m = 0; m < 4; ++m) _Pragma("unroll") for (int k = 0; k < 2; ++k) dst[m][k] = *(const PG8_LAS bf16x8*)(lds + PG8_SA(b, h) + aoff + m * 2048 + k * 1024); } while (0)
; #define PG8_LDB(dst, b, h) do { _Pragma("unroll") for (int n = 0; n < 2; ++n) _Pragma("unroll") for (int k = 0; k < 2; ++k) dst[n][k] = *(const PG8_LAS bf16x8*)(lds + PG8_SB(b, h) + boff + n * 2048 + k * 1024); } while (0)
; #define PG8_MMA(ai, bj, At, Bt) do { __builtin_amdgcn_s_setprio(1); _Pragma("unroll") for (int m = 0; m < 4; ++m) _Pragma("unroll") for (int n = 0; n < 2; ++n) _Pragma("unroll") for (int k = 0; k < 2; ++k) \
;         acc[ai][bj][m][n] = __builtin_amdgcn_mfma_f32_16x16x32_bf16(Bt[n][k], At[m][k], acc[ai][bj][m][n], 0, 0, 0); __builtin_amdgcn_s_setprio(0); } while (0)
; #define PG8_WAIT_V(n) asm volatile("s_waitcnt vmcnt(" #n ")" ::: "memory")
; #define PG8_WAIT_L(n) asm volatile("s_waitcnt lgkmcnt(" #n ")" ::: "memory")
; #define PG8_BAR __builtin_amdgcn_s_barrier()
; #define PG8_SCHED __builtin_amdgcn_sched_barrier(0)
; template <class Epi, class Sched, bool ALIGN_EPI = false, bool SP2 = false>
; __device__ __forceinline__ void gemm_phase(PG8_LAS unsigned char* lds, const Gemm g, const Sched& S, const Epi& E) {
;     ...
;             PG8_LDB(B0, 0, 0); PG8_LDB(B1, 0, 1); PG8_SCHED; PG8_LDA(At, 0, 0); PG8_STAGE(PG8_SA(1, 1), a1 + hstep, voffA);
;             PG8_WAIT_V(8); PG8_WAIT_L(0); PG8_BAR; PG8_MMA(0, 0, At, B0); PG8_MMA(0, 1, At, B1); PG8_BAR; PG8_SCHED;
;             PG8_LDA(At, 0, 1); PG8_STAGE(PG8_SB(0, 0), b2, voffB); PG8_STAGE(PG8_SB(0, 1), b2 + hstep, voffB); PG8_STAGE(PG8_SA(0, 0), a2, voffA);
.LBB0_265:
	s_add_u32 s10, s16, 0xfff80080
	s_addc_u32 s11, s17, -1
	s_add_i32 s27, 0, 0x10000
	s_cmp_eq_u32 s23, 28
	s_cselect_b32 s51, s5, s11
	s_cselect_b32 s50, s7, s10
	s_cselect_b32 s19, s8, s22
	s_cselect_b32 s18, s9, s15
	s_add_i32 s10, 0, 0x14000
	v_add_u32_e32 v168, s27, v157
	v_add_u32_e32 v184, s10, v157
	v_lshl_add_u64 v[200:201], s[16:17], 0, v[148:149]
	s_add_i32 m0, s57, 0xc000
	s_nop 0
	global_load_lds_dwordx4 v[200:201], off
	v_lshl_add_u64 v[200:201], s[16:17], 0, v[150:151]
	s_add_i32 m0, s57, 0xe000
	s_nop 0
	global_load_lds_dwordx4 v[200:201], off
	ds_read_b128 v[152:155], v168
	ds_read_b128 v[160:163], v168 offset:1024
	ds_read_b128 v[164:167], v168 offset:2048
	ds_read_b128 v[168:171], v168 offset:3072
	ds_read_b128 v[172:175], v184
	ds_read_b128 v[176:179], v184 offset:1024
	ds_read_b128 v[180:183], v184 offset:2048
	ds_read_b128 v[184:187], v184 offset:3072
	ds_read_b128 v[188:191], v159
	ds_read_b128 v[192:195], v159 offset:1024
	ds_read_b128 v[196:199], v159 offset:2048
	ds_read_b128 v[216:219], v159 offset:3072
	ds_read_b128 v[220:223], v159 offset:4096
	ds_read_b128 v[224:227], v159 offset:5120
	ds_read_b128 v[228:231], v159 offset:6144
	ds_read_b128 v[232:235], v159 offset:7168
	s_waitcnt vmcnt(8)
	s_waitcnt lgkmcnt(0)
	s_barrier
	s_setprio 1
	s_waitcnt lgkmcnt(0)
	v_mfma_f32_16x16x32_bf16 v[126:129], v[152:155], v[188:191], v[126:129]
	v_mfma_f32_16x16x32_bf16 v[122:125], v[164:167], v[188:191], v[122:125]
	v_mfma_f32_16x16x32_bf16 v[110:113], v[152:155], v[196:199], v[110:113]
	v_mfma_f32_16x16x32_bf16 v[106:109], v[164:167], v[196:199], v[106:109]
	v_mfma_f32_16x16x32_bf16 v[94:97], v[152:155], v[220:223], v[94:97]
	v_mfma_f32_16x16x32_bf16 v[90:93], v[164:167], v[220:223], v[90:93]
	v_mfma_f32_16x16x32_bf16 v[78:81], v[152:155], v[228:231], v[78:81]
	v_mfma_f32_16x16x32_bf16 v[74:77], v[164:167], v[228:231], v[74:77]
	v_mfma_f32_16x16x32_bf16 v[126:129], v[160:163], v[192:195], v[126:129]
	v_mfma_f32_16x16x32_bf16 v[122:125], v[168:171], v[192:195], v[122:125]
	v_mfma_f32_16x16x32_bf16 v[110:113], v[160:163], v[216:219], v[110:113]
	v_mfma_f32_16x16x32_bf16 v[106:109], v[168:171], v[216:219], v[106:109]
	v_mfma_f32_16x16x32_bf16 v[94:97], v[160:163], v[224:227], v[94:97]
	v_mfma_f32_16x16x32_bf16 v[90:93], v[168:171], v[224:227], v[90:93]
	v_mfma_f32_16x16x32_bf16 v[78:81], v[160:163], v[232:235], v[78:81]
	v_mfma_f32_16x16x32_bf16 v[74:77], v[168:171], v[232:235], v[74:77]
	s_setprio 0
	s_setprio 1
	v_mfma_f32_16x16x32_bf16 v[118:121], v[172:175], v[188:191], v[118:121]
	v_mfma_f32_16x16x32_bf16 v[114:117], v[180:183], v[188:191], v[114:117]
	v_mfma_f32_16x16x32_bf16 v[102:105], v[172:175], v[196:199], v[102:105]
	v_mfma_f32_16x16x32_bf16 v[98:101], v[180:183], v[196:199], v[98:101]
	v_mfma_f32_16x16x32_bf16 v[86:89], v[172:175], v[220:223], v[86:89]
	v_mfma_f32_16x16x32_bf16 v[82:85], v[180:183], v[220:223], v[82:85]
	v_mfma_f32_16x16x32_bf16 v[70:73], v[172:175], v[228:231], v[70:73]
	v_mfma_f32_16x16x32_bf16 v[66:69], v[180:183], v[228:231], v[66:69]
	v_mfma_f32_16x16x32_bf16 v[118:121], v[176:179], v[192:195], v[118:121]
	v_mfma_f32_16x16x32_bf16 v[114:117], v[184:187], v[192:195], v[114:117]
	v_mfma_f32_16x16x32_bf16 v[102:105], v[176:179], v[216:219], v[102:105]
	v_mfma_f32_16x16x32_bf16 v[98:101], v[184:187], v[216:219], v[98:101]
	v_mfma_f32_16x16x32_bf16 v[86:89], v[176:179], v[224:227], v[86:89]
	v_mfma_f32_16x16x32_bf16 v[82:85], v[184:187], v[224:227], v[82:85]
	v_mfma_f32_16x16x32_bf16 v[70:73], v[176:179], v[232:235], v[70:73]
	v_mfma_f32_16x16x32_bf16 v[66:69], v[184:187], v[232:235], v[66:69]
	s_setprio 0
	s_barrier
	s_add_i32 s11, s27, s56
	v_lshl_add_u64 v[200:201], s[18:19], 0, v[0:1]
	s_mov_b32 m0, s11
	s_nop 0
	global_load_lds_dwordx4 v[200:201], off
	s_add_i32 m0, s11, 0x2000
	s_add_u32 s38, s18, 0x80000
	v_lshl_add_u64 v[236:237], s[18:19], 0, v[142:143]
	s_addc_u32 s39, s19, 0
	s_add_i32 s10, s10, s56
	global_load_lds_dwordx4 v[236:237], off
	v_lshl_add_u64 v[238:239], s[38:39], 0, v[0:1]
	s_mov_b32 m0, s10
	v_lshl_add_u64 v[240:241], s[50:51], 0, v[144:145]
	global_load_lds_dwordx4 v[238:239], off
	v_lshl_add_u64 v[238:239], s[38:39], 0, v[142:143]
	s_add_i32 m0, s10, 0x2000
	s_nop 0
	global_load_lds_dwordx4 v[238:239], off
	v_lshl_add_u64 v[238:239], s[50:51], 0, v[146:147]
	s_mov_b32 m0, s57
	s_nop 0
	global_load_lds_dwordx4 v[238:239], off
	s_mov_b32 m0, s58
	s_nop 0
	global_load_lds_dwordx4 v[240:241], off
	ds_read_b128 v[188:191], v159 offset:16384
	ds_read_b128 v[192:195], v159 offset:17408
	ds_read_b128 v[196:199], v159 offset:18432
	ds_read_b128 v[216:219], v159 offset:19456
	ds_read_b128 v[220:223], v159 offset:20480
	ds_read_b128 v[224:227], v159 offset:21504
	ds_read_b128 v[228:231], v159 offset:22528
	ds_read_b128 v[232:235], v159 offset:23552
	s_waitcnt vmcnt(8)
	s_waitcnt lgkmcnt(0)
	s_barrier
; #define PG8_STAGE(bufoff, gbase, voff) do { _Pragma("unroll") for (int _i = 0; _i < 2; ++_i) \
;         __builtin_amdgcn_global_load_lds((const unsigned*)((const char*)(gbase) + (voff)[_i]), (PG8_LAS unsigned*)(lds + (bufoff) + ldsw + _i * 8192), 16, 0, 0); } while (0)
; #define PG8_LDA(dst, b, h) do { _Pragma("unroll") for (int m = 0; m < 4; ++m) _Pragma("unroll") for (int k = 0; k < 2; ++k) dst[m][k] = *(const PG8_LAS bf16x8*)(lds + PG8_SA(b, h) + aoff + m * 2048 + k * 1024); } while (0)
; #define PG8_LDB(dst, b, h) do { _Pragma("unroll") for (int n = 0; n < 2; ++n) _Pragma("unroll") for (int k = 0; k < 2; ++k) dst[n][k] = *(const PG8_LAS bf16x8*)(lds + PG8_SB(b, h) + boff + n * 2048 + k * 1024); } while (0)
; #define PG8_MMA(ai, bj, At, Bt) do { __builtin_amdgcn_s_setprio(1); _Pragma("unroll") for (int m = 0; m < 4; ++m) _Pragma("unroll") for (int n = 0; n < 2; ++n) _Pragma("unroll") for (int k = 0; k < 2; ++k) \
;         acc[ai][bj][m][n] = __builtin_amdgcn_mfma_f32_16x16x32_bf16(Bt[n][k], At[m][k], acc[ai][bj][m][n], 0, 0, 0); __builtin_amdgcn_s_setprio(0); } while (0)
; #define PG8_WAIT_V(n) asm volatile("s_waitcnt vmcnt(" #n ")" ::: "memory")
; #define PG8_WAIT_L(n) asm volatile("s_waitcnt lgkmcnt(" #n ")" ::: "memory")
; #define PG8_BAR __builtin_amdgcn_s_barrier()
; #define PG8_SCHED __builtin_amdgcn_sched_barrier(0)
; template <class Epi, class Sched, bool ALIGN_EPI = false, bool SP2 = false>
; __device__ __forceinline__ void gemm_phase(PG8_LAS unsigned char* lds, const Gemm g, const Sched& S, const Epi& E) {
;     ...
;             PG8_WAIT_V(8); PG8_WAIT_L(0); PG8_BAR; PG8_MMA(1, 0, At, B0); PG8_MMA(1, 1, At, B1); PG8_BAR; PG8_SCHED;
;             PG8_LDB(B0, 1, 0); PG8_LDB(B1, 1, 1); PG8_SCHED; PG8_LDA(At, 1, 0); PG8_STAGE(PG8_SA(0, 1), a2 + hstep, voffA);
;             PG8_WAIT_V(8); PG8_WAIT_L(0); PG8_BAR; PG8_MMA(0, 0, At, B0); PG8_MMA(0, 1, At, B1); PG8_BAR; PG8_SCHED;
	s_setprio 1
	s_waitcnt lgkmcnt(0)
	v_mfma_f32_16x16x32_bf16 v[62:65], v[152:155], v[188:191], v[62:65]
	v_mfma_f32_16x16x32_bf16 v[58:61], v[164:167], v[188:191], v[58:61]
	v_mfma_f32_16x16x32_bf16 v[50:53], v[152:155], v[196:199], v[50:53]
	v_mfma_f32_16x16x32_bf16 v[42:45], v[164:167], v[196:199], v[42:45]
	v_mfma_f32_16x16x32_bf16 v[34:37], v[152:155], v[220:223], v[34:37]
	v_mfma_f32_16x16x32_bf16 v[26:29], v[164:167], v[220:223], v[26:29]
	v_mfma_f32_16x16x32_bf16 v[18:21], v[152:155], v[228:231], v[18:21]
	v_mfma_f32_16x16x32_bf16 v[10:13], v[164:167], v[228:231], v[10:13]
	v_mfma_f32_16x16x32_bf16 v[62:65], v[160:163], v[192:195], v[62:65]
	v_mfma_f32_16x16x32_bf16 v[58:61], v[168:171], v[192:195], v[58:61]
	v_mfma_f32_16x16x32_bf16 v[50:53], v[160:163], v[216:219], v[50:53]
	v_mfma_f32_16x16x32_bf16 v[42:45], v[168:171], v[216:219], v[42:45]
	v_mfma_f32_16x16x32_bf16 v[34:37], v[160:163], v[224:227], v[34:37]
	v_mfma_f32_16x16x32_bf16 v[26:29], v[168:171], v[224:227], v[26:29]
	v_mfma_f32_16x16x32_bf16 v[18:21], v[160:163], v[232:235], v[18:21]
	v_mfma_f32_16x16x32_bf16 v[10:13], v[168:171], v[232:235], v[10:13]
	s_setprio 0
	s_setprio 1
	v_mfma_f32_16x16x32_bf16 v[54:57], v[172:175], v[188:191], v[54:57]
	v_mfma_f32_16x16x32_bf16 v[46:49], v[180:183], v[188:191], v[46:49]
	v_mfma_f32_16x16x32_bf16 v[38:41], v[172:175], v[196:199], v[38:41]
	v_mfma_f32_16x16x32_bf16 v[30:33], v[180:183], v[196:199], v[30:33]
	v_mfma_f32_16x16x32_bf16 v[22:25], v[172:175], v[220:223], v[22:25]
	v_mfma_f32_16x16x32_bf16 v[14:17], v[180:183], v[220:223], v[14:17]
	v_mfma_f32_16x16x32_bf16 v[6:9], v[172:175], v[228:231], v[6:9]
	v_mfma_f32_16x16x32_bf16 v[2:5], v[180:183], v[228:231], v[2:5]
	v_mfma_f32_16x16x32_bf16 v[54:57], v[176:179], v[192:195], v[54:57]
	v_mfma_f32_16x16x32_bf16 v[46:49], v[184:187], v[192:195], v[46:49]
	v_mfma_f32_16x16x32_bf16 v[38:41], v[176:179], v[216:219], v[38:41]
	v_mfma_f32_16x16x32_bf16 v[30:33], v[184:187], v[216:219], v[30:33]
	v_mfma_f32_16x16x32_bf16 v[22:25], v[176:179], v[224:227], v[22:25]
	v_mfma_f32_16x16x32_bf16 v[14:17], v[184:187], v[224:227], v[14:17]
	v_mfma_f32_16x16x32_bf16 v[6:9], v[176:179], v[232:235], v[6:9]
	v_mfma_f32_16x16x32_bf16 v[2:5], v[184:187], v[232:235], v[2:5]
	s_setprio 0
	s_barrier
	s_add_i32 s10, 0, 0x18000
	s_add_i32 s11, 0, 0x1c000
	v_add_u32_e32 v168, s10, v157
	v_add_u32_e32 v184, s11, v157
	s_add_u32 s38, s50, 0x80000
	s_addc_u32 s39, s51, 0
	s_mov_b32 m0, s59
	v_lshl_add_u64 v[242:243], s[38:39], 0, v[146:147]
	global_load_lds_dwordx4 v[242:243], off
	v_lshl_add_u64 v[242:243], s[38:39], 0, v[144:145]
	s_mov_b32 m0, s60
	s_nop 0
	global_load_lds_dwordx4 v[242:243], off
	ds_read_b128 v[152:155], v168
	ds_read_b128 v[160:163], v168 offset:1024
	ds_read_b128 v[164:167], v168 offset:2048
	ds_read_b128 v[168:171], v168 offset:3072
	ds_read_b128 v[172:175], v184
	ds_read_b128 v[176:179], v184 offset:1024
	ds_read_b128 v[180:183], v184 offset:2048
	ds_read_b128 v[184:187], v184 offset:3072
	ds_read_b128 v[188:191], v159 offset:32768
	ds_read_b128 v[192:195], v159 offset:33792
	ds_read_b128 v[196:199], v159 offset:34816
	ds_read_b128 v[216:219], v159 offset:35840
	ds_read_b128 v[220:223], v159 offset:36864
	ds_read_b128 v[224:227], v159 offset:37888
	ds_read_b128 v[228:231], v159 offset:38912
	ds_read_b128 v[232:235], v159 offset:39936
	s_waitcnt vmcnt(8)
	s_waitcnt lgkmcnt(0)
	s_barrier
	s_setprio 1
	s_waitcnt lgkmcnt(0)
	v_mfma_f32_16x16x32_bf16 v[126:129], v[152:155], v[188:191], v[126:129]
	v_mfma_f32_16x16x32_bf16 v[122:125], v[164:167], v[188:191], v[122:125]
	v_mfma_f32_16x16x32_bf16 v[110:113], v[152:155], v[196:199], v[110:113]
	v_mfma_f32_16x16x32_bf16 v[106:109], v[164:167], v[196:199], v[106:109]
	v_mfma_f32_16x16x32_bf16 v[94:97], v[152:155], v[220:223], v[94:97]
	v_mfma_f32_16x16x32_bf16 v[90:93], v[164:167], v[220:223], v[90:93]
	v_mfma_f32_16x16x32_bf16 v[78:81], v[152:155], v[228:231], v[78:81]
	v_mfma_f32_16x16x32_bf16 v[74:77], v[164:167], v[228:231], v[74:77]
	v_mfma_f32_16x16x32_bf16 v[126:129], v[160:163], v[192:195], v[126:129]
	v_mfma_f32_16x16x32_bf16 v[122:125], v[168:171], v[192:195], v[122:125]
	v_mfma_f32_16x16x32_bf16 v[110:113], v[160:163], v[216:219], v[110:113]
	v_mfma_f32_16x16x32_bf16 v[106:109], v[168:171], v[216:219], v[106:109]
	v_mfma_f32_16x16x32_bf16 v[94:97], v[160:163], v[224:227], v[94:97]
	v_mfma_f32_16x16x32_bf16 v[90:93], v[168:171], v[224:227], v[90:93]
	v_mfma_f32_16x16x32_bf16 v[78:81], v[160:163], v[232:235], v[78:81]
	v_mfma_f32_16x16x32_bf16 v[74:77], v[168:171], v[232:235], v[74:77]
	s_setprio 0
	s_setprio 1
	v_mfma_f32_16x16x32_bf16 v[118:121], v[172:175], v[188:191], v[118:121]
	v_mfma_f32_16x16x32_bf16 v[114:117], v[180:183], v[188:191], v[114:117]
	v_mfma_f32_16x16x32_bf16 v[102:105], v[172:175], v[196:199], v[102:105]
	v_mfma_f32_16x16x32_bf16 v[98:101], v[180:183], v[196:199], v[98:101]
	v_mfma_f32_16x16x32_bf16 v[86:89], v[172:175], v[220:223], v[86:89]
	v_mfma_f32_16x16x32_bf16 v[82:85], v[180:183], v[220:223], v[82:85]
	v_mfma_f32_16x16x32_bf16 v[70:73], v[172:175], v[228:231], v[70:73]
	v_mfma_f32_16x16x32_bf16 v[66:69], v[180:183], v[228:231], v[66:69]
	v_mfma_f32_16x16x32_bf16 v[118:121], v[176:179], v[192:195], v[118:121]
	v_mfma_f32_16x16x32_bf16 v[114:117], v[184:187], v[192:195], v[114:117]
	v_mfma_f32_16x16x32_bf16 v[102:105], v[176:179], v[216:219], v[102:105]
	v_mfma_f32_16x16x32_bf16 v[98:101], v[184:187], v[216:219], v[98:101]
	v_mfma_f32_16x16x32_bf16 v[86:89], v[176:179], v[224:227], v[86:89]
	v_mfma_f32_16x16x32_bf16 v[82:85], v[184:187], v[224:227], v[82:85]
	v_mfma_f32_16x16x32_bf16 v[70:73], v[176:179], v[232:235], v[70:73]
	v_mfma_f32_16x16x32_bf16 v[66:69], v[184:187], v[232:235], v[66:69]
	s_setprio 0
	s_barrier
; #define PG8_STAGE(bufoff, gbase, voff) do { _Pragma("unroll") for (int _i = 0; _i < 2; ++_i) \
;         __builtin_amdgcn_global_load_lds((const unsigned*)((const char*)(gbase) + (voff)[_i]), (PG8_LAS unsigned*)(lds + (bufoff) + ldsw + _i * 8192), 16, 0, 0); } while (0)
; #define PG8_LDA(dst, b, h) do { _Pragma("unroll") for (int m = 0; m < 4; ++m) _Pragma("unroll") for (int k = 0; k < 2; ++k) dst[m][k] = *(const PG8_LAS bf16x8*)(lds + PG8_SA(b, h) + aoff + m * 2048 + k * 1024); } while (0)
; #define PG8_MMA(ai, bj, At, Bt) do { __builtin_amdgcn_s_setprio(1); _Pragma("unroll") for (int m = 0; m < 4; ++m) _Pragma("unroll") for (int n = 0; n < 2; ++n) _Pragma("unroll") for (int k = 0; k < 2; ++k) \
;         acc[ai][bj][m][n] = __builtin_amdgcn_mfma_f32_16x16x32_bf16(Bt[n][k], At[m][k], acc[ai][bj][m][n], 0, 0, 0); __builtin_amdgcn_s_setprio(0); } while (0)
; #define PG8_WAIT_V(n) asm volatile("s_waitcnt vmcnt(" #n ")" ::: "memory")
; #define PG8_WAIT_L(n) asm volatile("s_waitcnt lgkmcnt(" #n ")" ::: "memory")
; #define PG8_BAR __builtin_amdgcn_s_barrier()
; #define PG8_SCHED __builtin_amdgcn_sched_barrier(0)
; template <class Epi, class Sched, bool ALIGN_EPI = false, bool SP2 = false>
; __device__ __forceinline__ void gemm_phase(PG8_LAS unsigned char* lds, const Gemm g, const Sched& S, const Epi& E) {
;     ...
;             PG8_LDA(At, 1, 1); PG8_STAGE(PG8_SB(1, 0), b3, voffB); PG8_STAGE(PG8_SB(1, 1), b3 + hstep, voffB); PG8_STAGE(PG8_SA(1, 0), a3, voffA);
;             PG8_WAIT_V(8); PG8_WAIT_L(0); PG8_BAR; PG8_MMA(1, 0, At, B0); PG8_MMA(1, 1, At, B1); PG8_BAR; PG8_SCHED;
;     ...
;         if constexpr (ALIGN_EPI) { if (wr == 0) PG8_BAR; }
	s_add_i32 s10, s10, s56
	v_lshl_add_u64 v[200:201], v[200:201], 0, s[30:31]
	s_mov_b32 m0, s10
	s_nop 0
	global_load_lds_dwordx4 v[200:201], off
	s_add_i32 m0, s10, 0x2000
	s_add_u32 s18, s18, 0x80080
	v_lshl_add_u64 v[200:201], v[236:237], 0, s[30:31]
	s_addc_u32 s19, s19, 0
	s_add_i32 s10, s11, s56
	global_load_lds_dwordx4 v[200:201], off
	v_lshl_add_u64 v[200:201], s[18:19], 0, v[0:1]
	s_mov_b32 m0, s10
	s_nop 0
	global_load_lds_dwordx4 v[200:201], off
	v_lshl_add_u64 v[200:201], s[18:19], 0, v[142:143]
	s_add_i32 m0, s10, 0x2000
	s_nop 0
	global_load_lds_dwordx4 v[200:201], off
	v_lshl_add_u64 v[200:201], v[238:239], 0, s[30:31]
	s_mov_b32 m0, s61
	s_nop 0
	global_load_lds_dwordx4 v[200:201], off
	v_lshl_add_u64 v[200:201], v[240:241], 0, s[30:31]
	s_mov_b32 m0, s62
	s_nop 0
	global_load_lds_dwordx4 v[200:201], off
	ds_read_b128 v[188:191], v159 offset:49152
	ds_read_b128 v[192:195], v159 offset:50176
	ds_read_b128 v[196:199], v159 offset:51200
	ds_read_b128 v[216:219], v159 offset:52224
	ds_read_b128 v[220:223], v159 offset:53248
	ds_read_b128 v[224:227], v159 offset:54272
	ds_read_b128 v[228:231], v159 offset:55296
	ds_read_b128 v[232:235], v159 offset:56320
	s_waitcnt vmcnt(8)
	s_waitcnt lgkmcnt(0)
	s_barrier
	s_setprio 1
	s_waitcnt lgkmcnt(0)
	v_mfma_f32_16x16x32_bf16 v[62:65], v[152:155], v[188:191], v[62:65]
	v_mfma_f32_16x16x32_bf16 v[58:61], v[164:167], v[188:191], v[58:61]
	v_mfma_f32_16x16x32_bf16 v[50:53], v[152:155], v[196:199], v[50:53]
	v_mfma_f32_16x16x32_bf16 v[42:45], v[164:167], v[196:199], v[42:45]
	v_mfma_f32_16x16x32_bf16 v[34:37], v[152:155], v[220:223], v[34:37]
	v_mfma_f32_16x16x32_bf16 v[26:29], v[164:167], v[220:223], v[26:29]
	v_mfma_f32_16x16x32_bf16 v[18:21], v[152:155], v[228:231], v[18:21]
	v_mfma_f32_16x16x32_bf16 v[10:13], v[164:167], v[228:231], v[10:13]
	v_mfma_f32_16x16x32_bf16 v[62:65], v[160:163], v[192:195], v[62:65]
	v_mfma_f32_16x16x32_bf16 v[58:61], v[168:171], v[192:195], v[58:61]
	v_mfma_f32_16x16x32_bf16 v[50:53], v[160:163], v[216:219], v[50:53]
	v_mfma_f32_16x16x32_bf16 v[42:45], v[168:171], v[216:219], v[42:45]
	v_mfma_f32_16x16x32_bf16 v[34:37], v[160:163], v[224:227], v[34:37]
	v_mfma_f32_16x16x32_bf16 v[26:29], v[168:171], v[224:227], v[26:29]
	v_mfma_f32_16x16x32_bf16 v[18:21], v[160:163], v[232:235], v[18:21]
	v_mfma_f32_16x16x32_bf16 v[10:13], v[168:171], v[232:235], v[10:13]
	s_setprio 0
	s_setprio 1
	v_mfma_f32_16x16x32_bf16 v[54:57], v[172:175], v[188:191], v[54:57]
	v_mfma_f32_16x16x32_bf16 v[46:49], v[180:183], v[188:191], v[46:49]
	v_mfma_f32_16x16x32_bf16 v[38:41], v[172:175], v[196:199], v[38:41]
	v_mfma_f32_16x16x32_bf16 v[30:33], v[180:183], v[196:199], v[30:33]
	v_mfma_f32_16x16x32_bf16 v[22:25], v[172:175], v[220:223], v[22:25]
	v_mfma_f32_16x16x32_bf16 v[14:17], v[180:183], v[220:223], v[14:17]
	v_mfma_f32_16x16x32_bf16 v[6:9], v[172:175], v[228:231], v[6:9]
	v_mfma_f32_16x16x32_bf16 v[2:5], v[180:183], v[228:231], v[2:5]
	v_mfma_f32_16x16x32_bf16 v[54:57], v[176:179], v[192:195], v[54:57]
	v_mfma_f32_16x16x32_bf16 v[46:49], v[184:187], v[192:195], v[46:49]
	v_mfma_f32_16x16x32_bf16 v[38:41], v[176:179], v[216:219], v[38:41]
	v_mfma_f32_16x16x32_bf16 v[30:33], v[184:187], v[216:219], v[30:33]
	v_mfma_f32_16x16x32_bf16 v[22:25], v[176:179], v[224:227], v[22:25]
	v_mfma_f32_16x16x32_bf16 v[14:17], v[184:187], v[224:227], v[14:17]
	v_mfma_f32_16x16x32_bf16 v[6:9], v[176:179], v[232:235], v[6:9]
	v_mfma_f32_16x16x32_bf16 v[2:5], v[184:187], v[232:235], v[2:5]
	s_setprio 0
	s_barrier
	s_add_i32 s23, s23, 2
	s_add_u32 s16, s16, 0x100
	s_addc_u32 s17, s17, 0
	s_add_u32 s15, s15, 0x100
	s_addc_u32 s22, s22, 0
	s_cmp_gt_u32 s23, 29
	s_cbranch_scc0 .LBB0_265
	s_and_b64 vcc, exec, s[24:25]
	s_cbranch_vccz .LBB0_268
	s_barrier
